# GEMM phase prologue: the second K-tile's staging loads are issued before the wait for the first K-tile (one exposed memory latency instead of two per phase start)
# baseline (speedup 1.0000x reference)
.LBB0_168:
	s_add_u32 s10, s28, 0x4c00000
	s_addc_u32 s11, s29, 0
	s_lshl_b32 s8, s8, 5
	s_mov_b64 s[24:25], 0x80
	s_and_b32 s34, s8, 0x60
	s_add_i32 m0, s46, 0x18000
	v_lshl_add_u64 v[2:3], v[2:3], 0, s[24:25]
	s_lshl_b32 s12, s7, 13
	s_lshl_b32 s13, s34, 7
	global_load_lds_dwordx4 v[2:3], off
	s_add_i32 m0, s46, 0x1a000
	s_add_u32 s8, s28, 0x4980080
	v_lshl_add_u64 v[0:1], v[0:1], 0, s[24:25]
	s_addc_u32 s9, s29, 0
	s_add_i32 s51, s46, 0x8000
	global_load_lds_dwordx4 v[0:1], off
	v_lshl_add_u64 v[0:1], s[8:9], 0, v[128:129]
	s_mov_b32 m0, s51
	s_add_i32 s52, s46, 0xa000
	global_load_lds_dwordx4 v[0:1], off
	v_lshl_add_u64 v[0:1], s[8:9], 0, v[132:133]
	s_add_u32 s8, s36, 0x40080
	s_mov_b32 m0, s52
	s_addc_u32 s9, s37, 0
	global_load_lds_dwordx4 v[0:1], off
	s_add_i32 m0, s46, 0x1c000
	v_lshl_add_u64 v[0:1], s[8:9], 0, v[130:131]
	global_load_lds_dwordx4 v[0:1], off
	v_lshl_add_u64 v[0:1], s[8:9], 0, v[134:135]
	s_add_i32 m0, s46, 0x1e000
	s_mov_b32 s30, 0xc000
	global_load_lds_dwordx4 v[0:1], off
	s_waitcnt vmcnt(8)
	s_barrier
	v_lshrrev_b32_e32 v1, 1, v8
	v_and_b32_e32 v3, 24, v1
	v_and_b32_e32 v0, 15, v8
	v_lshlrev_b32_e32 v1, 1, v3
	v_lshl_or_b32 v2, s7, 6, v0
	v_lshl_or_b32 v0, v0, 6, v1
	v_lshlrev_b32_e32 v1, 2, v8
	v_and_b32_e32 v1, 32, v1
	v_bitop3_b32 v8, v0, s12, v1 bitop3:0xde
	v_bitop3_b32 v158, v0, s13, v1 bitop3:0xde
	v_mov_b64_e32 v[0:1], s[10:11]
	s_movk_i32 s14, 0x88
	v_mad_i64_i32 v[136:137], s[8:9], v2, s30, v[0:1]
	v_or_b32_e32 v11, 16, v2
	v_cmp_gt_i32_e64 s[8:9], s14, v11
	v_mad_i64_i32 v[138:139], s[10:11], v11, s30, v[0:1]
	v_or_b32_e32 v11, 32, v2
	v_cmp_gt_i32_e64 s[10:11], s14, v11
	v_mad_i64_i32 v[140:141], s[12:13], v11, s30, v[0:1]
	v_or_b32_e32 v11, 48, v2
	s_cmpk_lt_u32 s6, 0x100
	v_cmp_gt_i32_e64 s[6:7], s14, v2
	v_cmp_gt_i32_e64 s[12:13], s14, v11
	v_mad_i64_i32 v[142:143], s[14:15], v11, s30, v[0:1]
	v_add_u32_e32 v11, 0x80, v2
	v_mad_i64_i32 v[144:145], s[16:17], v11, s30, v[0:1]
	v_add_u32_e32 v11, 0x90, v2
	v_mad_i64_i32 v[146:147], s[18:19], v11, s30, v[0:1]
	v_add_u32_e32 v11, 0xa0, v2
	v_mad_i64_i32 v[148:149], s[20:21], v11, s30, v[0:1]
	s_movk_i32 s18, 0xffe8
	s_movk_i32 s20, 0xffd8
	v_cmp_gt_i32_e64 s[14:15], 8, v2
	v_cmp_gt_i32_e64 s[16:17], -8, v2
	v_cmp_gt_i32_e64 s[18:19], s18, v2
	v_cmp_gt_i32_e64 s[20:21], s20, v2
	v_add_u32_e32 v2, 0xb0, v2
	v_mad_i64_i32 v[150:151], s[30:31], v2, s30, v[0:1]
	v_lshlrev_b32_e32 v0, 14, v4
	v_and_b32_e32 v0, 0xffff8000, v0
	v_lshl_add_u32 v0, v5, 11, v0
	v_and_b32_e32 v1, 1, v4
	v_lshl_or_b32 v0, v1, 6, v0
	v_lshl_add_u32 v0, v6, 1, v0
	v_mov_b32_e32 v1, v131
	v_lshl_add_u64 v[0:1], s[28:29], 0, v[0:1]
	s_mov_b64 s[30:31], 0x49c0080
	v_lshl_add_u64 v[152:153], v[0:1], 0, s[30:31]
	v_lshlrev_b32_e32 v0, 14, v7
	v_and_b32_e32 v0, 0xffff8000, v0
	v_lshl_add_u32 v0, v9, 11, v0
	v_and_b32_e32 v1, 1, v7
	v_lshl_or_b32 v0, v1, 6, v0
	s_waitcnt vmcnt(6)
	v_lshl_add_u32 v0, v10, 1, v0
	v_mov_b32_e32 v1, v131
	s_cselect_b64 s[26:27], -1, 0
	v_lshl_add_u64 v[0:1], s[28:29], 0, v[0:1]
	s_add_i32 s53, 0, 0x10000
	s_add_i32 s54, 0, 0x14000
	v_or_b32_e32 v159, s34, v3
	v_lshl_add_u64 v[154:155], v[0:1], 0, s[30:31]
	v_add_u32_e32 v160, s53, v158
	v_add_u32_e32 v161, s54, v158
	v_add_u32_e32 v162, 0, v8
	s_barrier
	s_branch .LBB0_171

.LBB0_320:
	s_lshl_b32 s18, s25, 5
	s_and_b32 s62, s18, 0x60
	s_add_i32 m0, s58, 0x18000
	v_lshl_add_u64 v[6:7], v[6:7], 0, s[8:9]
	s_lshl_b32 s21, s24, 13
	s_lshl_b32 s22, s62, 7
	global_load_lds_dwordx4 v[6:7], off
	v_lshl_add_u64 v[4:5], v[4:5], 0, s[8:9]
	s_add_i32 m0, s58, 0x1a000
	s_add_i32 s63, s58, 0x8000
	s_add_i32 s64, s58, 0xa000
	global_load_lds_dwordx4 v[4:5], off
	v_lshl_add_u64 v[0:1], v[0:1], 0, s[8:9]
	s_mov_b32 m0, s63
	s_add_u32 s18, s36, 0x40080
	global_load_lds_dwordx4 v[0:1], off
	v_lshl_add_u64 v[0:1], v[2:3], 0, s[8:9]
	s_mov_b32 m0, s64
	s_addc_u32 s19, s37, 0
	global_load_lds_dwordx4 v[0:1], off
	s_add_i32 m0, s58, 0x1c000
	v_lshl_add_u64 v[0:1], s[18:19], 0, v[132:133]
	global_load_lds_dwordx4 v[0:1], off
	v_lshl_add_u64 v[0:1], s[18:19], 0, v[136:137]
	s_add_i32 m0, s58, 0x1e000
	s_cmpk_lt_u32 s6, 0x100
	global_load_lds_dwordx4 v[0:1], off
	s_waitcnt vmcnt(8)
	s_barrier
	v_lshrrev_b32_e32 v1, 1, v8
	v_and_b32_e32 v138, 24, v1
	v_and_b32_e32 v0, 15, v8
	v_lshlrev_b32_e32 v1, 1, v138
	v_lshl_or_b32 v144, s24, 6, v0
	v_lshl_or_b32 v0, v0, 6, v1
	v_lshlrev_b32_e32 v1, 2, v8
	v_and_b32_e32 v1, 32, v1
	v_bitop3_b32 v2, v0, s21, v1 bitop3:0xde
	v_bitop3_b32 v145, v0, s22, v1 bitop3:0xde
	v_cvt_f32_ubyte0_e32 v0, s13
	v_rcp_iflag_f32_e32 v0, v0
	s_cselect_b64 s[18:19], -1, 0
	s_lshl_b32 s69, s13, 3
	v_cvt_f32_ubyte0_e32 v1, s69
	v_mul_f32_e32 v0, 0x4f7ffffe, v0
	v_cvt_u32_f32_e32 v0, v0
	v_rcp_iflag_f32_e32 v1, v1
	s_sub_i32 s21, 0, s13
	s_waitcnt vmcnt(6)
	v_readfirstlane_b32 s22, v0
	v_mul_f32_e32 v0, 0x4f7ffffe, v1
	v_cvt_u32_f32_e32 v0, v0
	s_mul_i32 s21, s21, s22
	s_mul_hi_u32 s21, s22, s21
	s_add_i32 s70, s22, s21
	v_readfirstlane_b32 s22, v0
	v_lshlrev_b32_e32 v0, 14, v9
	v_and_b32_e32 v0, 0xffff8000, v0
	v_lshl_add_u32 v0, v10, 11, v0
	v_and_b32_e32 v1, 1, v9
	v_lshl_or_b32 v0, v1, 6, v0
	v_lshl_add_u32 v140, v11, 1, v0
	v_lshlrev_b32_e32 v0, 14, v12
	s_sub_i32 s21, 0, s69
	v_and_b32_e32 v0, 0xffff8000, v0
	s_lshr_b32 s65, s13, 3
	s_mul_i32 s21, s21, s22
	v_lshl_add_u32 v0, v13, 11, v0
	v_and_b32_e32 v1, 1, v12
	s_and_b32 s66, s13, 4
	s_add_i32 s67, s65, 1
	s_mul_hi_u32 s21, s22, s21
	v_lshl_or_b32 v0, v1, 6, v0
	s_mul_i32 s68, s67, s66
	s_mov_b32 s6, 0
	s_add_i32 s71, s22, s21
	v_mov_b32_e32 v141, v129
	v_lshl_add_u32 v142, v14, 1, v0
	v_mov_b32_e32 v143, v129
	v_add_u32_e32 v146, 0, v2
	s_mov_b64 s[34:35], s[14:15]
	s_mov_b32 s72, 0
	s_barrier
	s_branch .LBB0_323

.LBB0_419:
	s_add_u32 s16, s12, 0x10f70000
	s_addc_u32 s17, s13, 0
	s_and_b32 s48, s19, 3
	s_add_i32 m0, s44, 0x18000
	v_lshl_add_u64 v[6:7], v[6:7], 0, s[4:5]
	s_lshl_b32 s19, s20, 13
	s_lshl_b32 s21, s48, 12
	global_load_lds_dwordx4 v[6:7], off
	v_lshl_add_u64 v[4:5], v[4:5], 0, s[4:5]
	s_add_i32 m0, s44, 0x1a000
	s_add_i32 s49, s44, 0x8000
	s_add_i32 s50, s44, 0xa000
	global_load_lds_dwordx4 v[4:5], off
	v_lshl_add_u64 v[0:1], v[0:1], 0, s[4:5]
	s_mov_b32 m0, s49
	s_add_u32 s22, s38, 0x40080
	global_load_lds_dwordx4 v[0:1], off
	v_lshl_add_u64 v[0:1], v[2:3], 0, s[4:5]
	s_mov_b32 m0, s50
	s_addc_u32 s23, s39, 0
	global_load_lds_dwordx4 v[0:1], off
	s_add_i32 m0, s44, 0x1c000
	v_lshl_add_u64 v[0:1], s[22:23], 0, v[184:185]
	global_load_lds_dwordx4 v[0:1], off
	v_lshl_add_u64 v[0:1], s[22:23], 0, v[148:149]
	s_add_i32 m0, s44, 0x1e000
	v_bfe_u32 v2, v8, 4, 2
	global_load_lds_dwordx4 v[0:1], off
	s_waitcnt vmcnt(8)
	s_barrier
	v_and_b32_e32 v1, 15, v8
	v_lshlrev_b32_e32 v0, 4, v2
	v_lshlrev_b32_e32 v4, 2, v8
	v_lshl_or_b32 v166, s20, 6, v1
	v_lshl_or_b32 v1, v1, 6, v0
	v_and_b32_e32 v4, 32, v4
	v_bitop3_b32 v5, v1, s19, v4 bitop3:0xde
	v_bitop3_b32 v167, v1, s21, v4 bitop3:0xde
	v_mov_b32_e32 v1, v185
	v_lshl_add_u64 v[150:151], s[10:11], 0, v[0:1]
	v_lshlrev_b32_e32 v0, 14, v9
	v_and_b32_e32 v0, 0xffff8000, v0
	v_lshl_add_u32 v0, v10, 11, v0
	v_and_b32_e32 v1, 1, v9
	v_lshl_or_b32 v0, v1, 6, v0
	v_lshl_add_u32 v152, v11, 1, v0
	v_lshlrev_b32_e32 v0, 14, v12
	v_and_b32_e32 v0, 0xffff8000, v0
	s_waitcnt vmcnt(6)
	s_cmpk_lt_u32 s18, 0x100
	v_readlane_b32 s20, v243, 56
	v_lshl_add_u32 v0, v13, 11, v0
	v_and_b32_e32 v1, 1, v12
	v_lshlrev_b32_e32 v3, 3, v2
	s_cselect_b64 s[18:19], -1, 0
	s_lshl_b32 s61, s20, 9
	v_lshl_or_b32 v0, v1, 6, v0
	v_lshl_or_b32 v168, s48, 5, v3
	s_mov_b32 s51, 0
	v_cmp_eq_u32_e64 s[72:73], 0, v2
	s_lshl_b32 s52, s20, 2
	s_add_i32 s53, s61, 0x2000
	s_lshl_b32 s54, s20, 13
	s_add_i32 s55, s61, 0x2010
	s_add_i32 s56, s61, 0x2020
	s_add_i32 s57, s61, 0x2030
	s_add_i32 s58, s61, 0x2080
	s_add_i32 s59, s61, 0x2090
	s_add_i32 s60, s61, 0x20a0
	s_addk_i32 s61, 0x20b0
	v_mov_b32_e32 v153, v185
	v_lshl_add_u32 v154, v14, 1, v0
	v_mov_b32_e32 v155, v185
	v_add_u32_e32 v169, 0, v5
	s_barrier
	s_branch .LBB0_422

.LBB0_568:
	s_lshl_b32 s16, s16, 5
	s_and_b32 s19, s16, 0x60
	s_add_i32 m0, s34, 0x18000
	v_lshl_add_u64 v[6:7], v[6:7], 0, s[4:5]
	s_lshl_b32 s18, s15, 13
	s_lshl_b32 s20, s19, 7
	global_load_lds_dwordx4 v[6:7], off
	v_lshl_add_u64 v[4:5], v[4:5], 0, s[4:5]
	s_add_i32 m0, s34, 0x1a000
	s_add_i32 s38, s34, 0x8000
	s_add_i32 s39, s34, 0xa000
	global_load_lds_dwordx4 v[4:5], off
	v_lshl_add_u64 v[0:1], v[0:1], 0, s[4:5]
	s_mov_b32 m0, s38
	s_add_u32 s16, s26, 0x20080
	global_load_lds_dwordx4 v[0:1], off
	v_lshl_add_u64 v[0:1], v[2:3], 0, s[4:5]
	s_mov_b32 m0, s39
	s_addc_u32 s17, s27, 0
	global_load_lds_dwordx4 v[0:1], off
	s_add_i32 m0, s34, 0x1c000
	v_lshl_add_u64 v[0:1], s[16:17], 0, v[184:185]
	global_load_lds_dwordx4 v[0:1], off
	v_lshl_add_u64 v[0:1], s[16:17], 0, v[160:161]
	s_add_i32 m0, s34, 0x1e000
	v_bfe_u32 v2, v8, 4, 2
	global_load_lds_dwordx4 v[0:1], off
	s_waitcnt vmcnt(8)
	s_barrier
	v_and_b32_e32 v1, 15, v8
	v_lshlrev_b32_e32 v0, 4, v2
	v_lshlrev_b32_e32 v3, 2, v8
	v_lshl_or_b32 v181, s15, 6, v1
	v_lshl_or_b32 v1, v1, 6, v0
	v_and_b32_e32 v3, 32, v3
	v_bitop3_b32 v4, v1, s18, v3 bitop3:0xde
	v_bitop3_b32 v182, v1, s20, v3 bitop3:0xde
	v_mov_b32_e32 v1, v185
	v_lshl_add_u64 v[166:167], s[10:11], 0, v[0:1]
	v_lshl_or_b32 v0, v2, 3, s19
	v_or_b32_e32 v183, 0x1800, v0
	v_lshlrev_b32_e32 v0, 13, v13
	v_and_b32_e32 v0, 0xffffc000, v0
	v_lshl_add_u32 v0, v12, 10, v0
	v_and_b32_e32 v1, 1, v13
	v_lshl_or_b32 v0, v1, 6, v0
	v_lshl_add_u32 v168, v14, 1, v0
	v_lshlrev_b32_e32 v0, 13, v9
	v_and_b32_e32 v0, 0xffffc000, v0
	s_waitcnt vmcnt(6)
	s_cmpk_lt_u32 s14, 0x100
	v_readlane_b32 s10, v243, 56
	v_lshl_add_u32 v0, v10, 10, v0
	v_and_b32_e32 v1, 1, v9
	s_cselect_b64 s[14:15], -1, 0
	s_lshl_b32 s48, s10, 9
	s_lshl_b32 s41, s10, 13
	v_lshl_or_b32 v0, v1, 6, v0
	v_readlane_b32 s10, v244, 59
	s_add_i32 s40, s48, 0x2000
	s_add_i32 s42, s48, 0x2010
	s_add_i32 s43, s48, 0x2020
	s_add_i32 s44, s48, 0x2030
	s_add_i32 s45, s48, 0x2080
	s_add_i32 s46, s48, 0x2090
	s_add_i32 s47, s48, 0x20a0
	s_addk_i32 s48, 0x20b0
	v_mov_b32_e32 v169, v185
	v_lshl_add_u32 v170, v11, 1, v0
	v_mov_b32_e32 v171, v185
	s_mov_b32 s49, 0
	v_add_u32_e32 v186, 0, v4
	v_readlane_b32 s50, v243, 1
	s_mov_b32 s51, s10
	s_barrier
	v_readlane_b32 s11, v244, 60
	s_branch .LBB0_571

.LBB0_902:
	s_lshl_b32 s12, s12, 5
	s_and_b32 s15, s12, 0x60
	s_add_i32 m0, s28, 0x18000
	v_lshl_add_u64 v[6:7], v[6:7], 0, s[4:5]
	s_lshl_b32 s14, s11, 13
	s_lshl_b32 s16, s15, 7
	global_load_lds_dwordx4 v[6:7], off
	v_lshl_add_u64 v[4:5], v[4:5], 0, s[4:5]
	s_add_i32 m0, s28, 0x1a000
	s_add_i32 s34, s28, 0x8000
	s_add_i32 s35, s28, 0xa000
	global_load_lds_dwordx4 v[4:5], off
	v_lshl_add_u64 v[0:1], v[0:1], 0, s[4:5]
	s_mov_b32 m0, s34
	s_add_u32 s12, s22, 0x40080
	global_load_lds_dwordx4 v[0:1], off
	v_lshl_add_u64 v[0:1], v[2:3], 0, s[4:5]
	s_mov_b32 m0, s35
	s_addc_u32 s13, s23, 0
	global_load_lds_dwordx4 v[0:1], off
	s_add_i32 m0, s28, 0x1c000
	v_lshl_add_u64 v[0:1], s[12:13], 0, v[132:133]
	global_load_lds_dwordx4 v[0:1], off
	v_lshl_add_u64 v[0:1], s[12:13], 0, v[128:129]
	s_add_i32 m0, s28, 0x1e000
	s_mov_b64 s[18:19], 0x240080
	global_load_lds_dwordx4 v[0:1], off
	s_waitcnt vmcnt(8)
	s_barrier
	v_lshrrev_b32_e32 v0, 1, v8
	v_and_b32_e32 v0, 24, v0
	v_and_b32_e32 v1, 15, v8
	v_lshlrev_b32_e32 v2, 1, v0
	v_lshl_or_b32 v142, s11, 6, v1
	v_lshl_or_b32 v1, v1, 6, v2
	v_lshlrev_b32_e32 v2, 2, v8
	v_and_b32_e32 v2, 32, v2
	v_bitop3_b32 v4, v1, s14, v2 bitop3:0xde
	s_movk_i32 s14, 0x2400
	v_bitop3_b32 v143, v1, s16, v2 bitop3:0xde
	v_lshrrev_b32_e32 v1, 1, v14
	v_mul_lo_u32 v2, v13, s14
	s_mov_b32 s16, 0x24000
	v_mad_u64_u32 v[2:3], s[12:13], v1, s16, v[2:3]
	v_or_b32_e32 v1, v2, v15
	v_add_lshl_u32 v184, v1, v16, 1
	v_lshrrev_b32_e32 v1, 1, v9
	v_mul_lo_u32 v2, v10, s14
	v_mad_u64_u32 v[2:3], s[12:13], v1, s16, v[2:3]
	s_waitcnt vmcnt(6)
	v_or_b32_e32 v1, v2, v11
	s_cmpk_lt_u32 s10, 0x100
	v_lshl_add_u64 v[136:137], v[184:185], 0, s[18:19]
	v_add_lshl_u32 v184, v1, v12, 1
	v_readlane_b32 s12, v244, 5
	s_cselect_b64 s[10:11], -1, 0
	v_or_b32_e32 v144, 16, v142
	v_or_b32_e32 v145, 32, v142
	v_or_b32_e32 v146, 48, v142
	v_lshl_add_u64 v[138:139], v[184:185], 0, s[18:19]
	s_mov_b32 s36, 0
	v_add_u32_e32 v147, 0, v4
	s_lshl_b32 s96, s15, 1
	v_lshlrev_b32_e32 v184, 1, v0
	s_mov_b32 s39, s12
	v_readlane_b32 s38, v243, 4
	v_readlane_b32 s40, v243, 2
	s_barrier
	v_readlane_b32 s13, v244, 6
	s_branch .LBB0_905

.LBB0_1041:
	s_lshl_b64 s[12:13], s[66:67], 2
	s_add_u32 s12, s82, s12
	s_addc_u32 s13, s83, s13
	s_add_u32 s12, s12, 0x4c02000
	s_addc_u32 s13, s13, 0
	s_lshl_b32 s14, s70, 1
	s_or_b32 s14, s14, 1
	s_mul_hi_i32 s15, s14, 0x88000
	s_mul_i32 s14, s14, 0x88000
	s_add_u32 s14, s82, s14
	s_addc_u32 s15, s83, s15
	s_add_u32 s14, s14, 0x5260000
	s_addc_u32 s15, s15, 0
	s_add_u32 s16, s82, 0x6570000
	s_addc_u32 s17, s83, 0
	v_bfe_u32 v18, v16, 4, 2
	s_add_u32 s18, s82, 0x62d8000
	v_and_b32_e32 v17, 15, v16
	v_lshlrev_b32_e32 v20, 4, v18
	v_lshlrev_b32_e32 v16, 2, v16
	s_addc_u32 s19, s83, 0
	s_and_b32 s46, s21, 3
	v_lshl_or_b32 v186, s22, 6, v17
	v_lshl_or_b32 v17, v17, 6, v20
	s_lshl_b32 s21, s22, 13
	v_and_b32_e32 v16, 32, v16
	s_add_i32 m0, s42, 0x18000
	v_lshl_add_u64 v[6:7], v[6:7], 0, s[4:5]
	v_bitop3_b32 v20, v17, s21, v16 bitop3:0xde
	s_lshl_b32 s21, s46, 12
	global_load_lds_dwordx4 v[6:7], off
	v_lshl_add_u64 v[4:5], v[4:5], 0, s[4:5]
	s_add_i32 m0, s42, 0x1a000
	s_add_i32 s47, s42, 0x8000
	s_add_i32 s48, s42, 0xa000
	global_load_lds_dwordx4 v[4:5], off
	v_lshl_add_u64 v[0:1], v[0:1], 0, s[4:5]
	s_mov_b32 m0, s47
	s_add_u32 s22, s34, 0x40080
	global_load_lds_dwordx4 v[0:1], off
	v_lshl_add_u64 v[0:1], v[2:3], 0, s[4:5]
	s_mov_b32 m0, s48
	s_addc_u32 s23, s35, 0
	global_load_lds_dwordx4 v[0:1], off
	s_add_i32 m0, s42, 0x1c000
	v_lshl_add_u64 v[0:1], s[22:23], 0, v[162:163]
	global_load_lds_dwordx4 v[0:1], off
	v_lshl_add_u64 v[0:1], s[22:23], 0, v[166:167]
	s_add_i32 m0, s42, 0x1e000
	s_movk_i32 s24, 0x2400
	global_load_lds_dwordx4 v[0:1], off
	s_waitcnt vmcnt(8)
	s_barrier
	s_cmpk_lt_u32 s20, 0x100
	v_readlane_b32 s22, v243, 56
	v_lshrrev_b32_e32 v1, 1, v8
	v_mul_lo_u32 v0, v10, s24
	s_mov_b32 s25, 0x24000
	v_bitop3_b32 v187, v17, s21, v16 bitop3:0xde
	s_cselect_b64 s[20:21], -1, 0
	s_lshl_b32 s58, s22, 9
	s_lshl_b32 s51, s22, 13
	v_mad_u64_u32 v[0:1], s[22:23], v1, s25, v[0:1]
	v_or_b32_e32 v0, v0, v9
	v_add_lshl_u32 v184, v0, v11, 1
	v_lshrrev_b32_e32 v1, 1, v12
	v_mul_lo_u32 v0, v14, s24
	v_mad_u64_u32 v[0:1], s[22:23], v1, s25, v[0:1]
	s_waitcnt vmcnt(6)
	s_mov_b64 s[26:27], 0x240080
	v_or_b32_e32 v0, v0, v13
	v_lshlrev_b32_e32 v19, 3, v18
	v_lshl_add_u64 v[168:169], v[184:185], 0, s[26:27]
	v_add_lshl_u32 v184, v0, v15, 1
	v_lshl_or_b32 v188, s46, 5, v19
	s_mov_b32 s49, 0
	v_cmp_eq_u32_e64 s[72:73], 0, v18
	s_add_i32 s50, s58, 0x2000
	s_add_i32 s52, s58, 0x2010
	s_add_i32 s53, s58, 0x2020
	s_add_i32 s54, s58, 0x2030
	s_add_i32 s55, s58, 0x2080
	s_add_i32 s56, s58, 0x2090
	s_add_i32 s57, s58, 0x20a0
	s_addk_i32 s58, 0x20b0
	v_lshl_add_u64 v[170:171], v[184:185], 0, s[26:27]
	v_add_u32_e32 v189, 0, v20
	s_barrier
	s_branch .LBB0_1044

.LBB0_1220:
	s_add_u32 s12, s18, 0x7670000
	s_addc_u32 s13, s19, 0
	s_lshl_b64 s[14:15], s[6:7], 2
	s_add_u32 s14, s18, s14
	s_addc_u32 s15, s19, s15
	s_add_u32 s14, s14, 0x5e10000
	s_addc_u32 s15, s15, 0
	s_and_b32 s22, s20, 3
	s_add_i32 m0, s38, 0x18000
	v_lshl_add_u64 v[6:7], v[6:7], 0, s[4:5]
	s_lshl_b32 s23, s17, 13
	s_lshl_b32 s24, s22, 12
	global_load_lds_dwordx4 v[6:7], off
	v_lshl_add_u64 v[4:5], v[4:5], 0, s[4:5]
	s_add_i32 m0, s38, 0x1a000
	s_add_i32 s42, s38, 0x8000
	s_add_i32 s43, s38, 0xa000
	global_load_lds_dwordx4 v[4:5], off
	v_lshl_add_u64 v[0:1], v[0:1], 0, s[4:5]
	s_mov_b32 m0, s42
	s_add_u32 s20, s30, 0x40080
	global_load_lds_dwordx4 v[0:1], off
	v_lshl_add_u64 v[0:1], v[2:3], 0, s[4:5]
	s_mov_b32 m0, s43
	s_addc_u32 s21, s31, 0
	global_load_lds_dwordx4 v[0:1], off
	s_add_i32 m0, s38, 0x1c000
	v_lshl_add_u64 v[0:1], s[20:21], 0, v[184:185]
	global_load_lds_dwordx4 v[0:1], off
	v_lshl_add_u64 v[0:1], s[20:21], 0, v[144:145]
	s_add_i32 m0, s38, 0x1e000
	v_lshlrev_b32_e32 v3, 2, v8
	global_load_lds_dwordx4 v[0:1], off
	s_waitcnt vmcnt(8)
	s_barrier
	v_bfe_u32 v0, v8, 4, 2
	v_and_b32_e32 v1, 15, v8
	v_lshlrev_b32_e32 v2, 3, v0
	v_lshlrev_b32_e32 v0, 4, v0
	v_lshl_or_b32 v160, s17, 6, v1
	v_lshl_or_b32 v1, v1, 6, v0
	v_and_b32_e32 v3, 32, v3
	v_bitop3_b32 v4, v1, s23, v3 bitop3:0xde
	v_bitop3_b32 v161, v1, s24, v3 bitop3:0xde
	v_mov_b32_e32 v1, v185
	v_lshl_add_u64 v[0:1], s[18:19], 0, v[0:1]
	s_mov_b64 s[18:19], 0x62d8000
	v_lshl_add_u64 v[150:151], v[0:1], 0, s[18:19]
	v_lshlrev_b32_e32 v0, 14, v13
	v_and_b32_e32 v0, 0xffff8000, v0
	v_lshl_add_u32 v0, v12, 11, v0
	v_and_b32_e32 v1, 1, v13
	v_lshl_or_b32 v0, v1, 6, v0
	v_lshl_add_u32 v152, v14, 1, v0
	v_lshlrev_b32_e32 v0, 14, v9
	v_and_b32_e32 v0, 0xffff8000, v0
	s_waitcnt vmcnt(6)
	s_cmpk_lt_u32 s16, 0x100
	v_readlane_b32 s18, v243, 56
	v_lshl_add_u32 v0, v10, 11, v0
	v_and_b32_e32 v1, 1, v9
	s_cselect_b64 s[16:17], -1, 0
	s_lshl_b32 s44, s18, 9
	s_lshl_b32 s45, s18, 13
	v_lshl_or_b32 v0, v1, 6, v0
	v_readlane_b32 s18, v244, 50
	v_lshl_or_b32 v162, s22, 5, v2
	v_or_b32_e32 v163, 16, v160
	v_or_b32_e32 v164, 32, v160
	v_or_b32_e32 v165, 48, v160
	s_addk_i32 s44, 0x2000
	v_mov_b32_e32 v153, v185
	v_lshl_add_u32 v154, v11, 1, v0
	v_mov_b32_e32 v155, v185
	s_mov_b32 s46, 0
	v_add_u32_e32 v166, 0, v4
	v_readlane_b32 s48, v244, 39
	s_mov_b32 s47, s18
	s_barrier
	v_readlane_b32 s19, v244, 51
	s_branch .LBB0_1223

.LBB0_1312:
	v_bfe_u32 v150, v13, 4, 2
	v_and_b32_e32 v145, 15, v13
	v_lshlrev_b32_e32 v146, 4, v150
	v_lshlrev_b32_e32 v13, 2, v13
	s_and_b32 s1, s1, 3
	v_lshl_or_b32 v15, v145, 6, v146
	s_lshl_b32 s12, s0, 13
	v_and_b32_e32 v13, 32, v13
	s_add_i32 m0, s19, 0x18000
	v_lshl_add_u64 v[6:7], v[6:7], 0, s[4:5]
	v_bitop3_b32 v16, v15, s12, v13 bitop3:0xde
	s_lshl_b32 s12, s1, 12
	global_load_lds_dwordx4 v[6:7], off
	v_lshl_add_u64 v[4:5], v[4:5], 0, s[4:5]
	s_add_i32 m0, s19, 0x1a000
	s_add_i32 s24, s19, 0x8000
	s_add_i32 s25, s19, 0xa000
	v_bitop3_b32 v122, v15, s12, v13 bitop3:0xde
	global_load_lds_dwordx4 v[4:5], off
	v_lshl_add_u64 v[2:3], v[2:3], 0, s[4:5]
	s_mov_b32 m0, s24
	s_add_u32 s12, s8, 0x40080
	global_load_lds_dwordx4 v[2:3], off
	v_lshl_add_u64 v[0:1], v[0:1], 0, s[4:5]
	s_mov_b32 m0, s25
	s_addc_u32 s13, s9, 0
	global_load_lds_dwordx4 v[0:1], off
	s_add_i32 m0, s19, 0x1c000
	v_lshl_add_u64 v[0:1], s[12:13], 0, v[184:185]
	global_load_lds_dwordx4 v[0:1], off
	v_lshl_add_u64 v[0:1], s[12:13], 0, v[108:109]
	s_add_i32 m0, s19, 0x1e000
	v_readlane_b32 s12, v243, 7
	global_load_lds_dwordx4 v[0:1], off
	s_waitcnt vmcnt(8)
	s_barrier
	v_lshlrev_b32_e32 v0, 14, v8
	v_and_b32_e32 v0, 0xffff8000, v0
	v_lshl_add_u32 v0, v9, 11, v0
	v_and_b32_e32 v1, 1, v8
	v_readlane_b32 s13, v243, 8
	s_add_u32 s12, s36, s12
	v_lshl_or_b32 v0, v1, 6, v0
	s_addc_u32 s13, s37, s13
	v_lshl_add_u32 v0, v10, 1, v0
	v_mov_b32_e32 v1, v185
	v_lshl_add_u64 v[110:111], s[12:13], 0, v[0:1]
	v_lshlrev_b32_e32 v0, 14, v11
	v_and_b32_e32 v0, 0xffff8000, v0
	v_lshl_add_u32 v0, v12, 11, v0
	v_and_b32_e32 v1, 1, v11
	v_lshl_or_b32 v0, v1, 6, v0
	s_waitcnt vmcnt(6)
	v_lshl_add_u32 v0, v14, 1, v0
	v_mov_b32_e32 v1, v185
	v_lshl_add_u64 v[120:121], s[12:13], 0, v[0:1]
	v_mov_b32_e32 v0, 0
	v_lshl_or_b32 v151, s0, 6, v145
	s_mov_b32 s26, -2
	s_mov_b64 s[12:13], 0x75b0080
	v_add_u32_e32 v123, 0, v16
	v_mov_b32_e32 v1, v0
	v_mov_b32_e32 v2, v0
	v_mov_b32_e32 v3, v0
	v_mov_b32_e32 v4, v0
	v_mov_b32_e32 v5, v0
	v_mov_b32_e32 v6, v0
	v_mov_b32_e32 v7, v0
	v_mov_b32_e32 v16, v0
	v_mov_b32_e32 v17, v0
	v_mov_b32_e32 v18, v0
	v_mov_b32_e32 v19, v0
	v_mov_b32_e32 v20, v0
	v_mov_b32_e32 v21, v0
	v_mov_b32_e32 v22, v0
	v_mov_b32_e32 v23, v0
	v_mov_b32_e32 v32, v0
	v_mov_b32_e32 v33, v0
	v_mov_b32_e32 v34, v0
	v_mov_b32_e32 v35, v0
	v_mov_b32_e32 v36, v0
	v_mov_b32_e32 v37, v0
	v_mov_b32_e32 v38, v0
	v_mov_b32_e32 v39, v0
	v_mov_b32_e32 v48, v0
	v_mov_b32_e32 v49, v0
	v_mov_b32_e32 v50, v0
	v_mov_b32_e32 v51, v0
	v_mov_b32_e32 v52, v0
	v_mov_b32_e32 v53, v0
	v_mov_b32_e32 v54, v0
	v_mov_b32_e32 v55, v0
	v_mov_b32_e32 v8, v0
	v_mov_b32_e32 v9, v0
	v_mov_b32_e32 v10, v0
	v_mov_b32_e32 v11, v0
	v_mov_b32_e32 v12, v0
	v_mov_b32_e32 v13, v0
	v_mov_b32_e32 v14, v0
	v_mov_b32_e32 v15, v0
	v_mov_b32_e32 v24, v0
	v_mov_b32_e32 v25, v0
	v_mov_b32_e32 v26, v0
	v_mov_b32_e32 v27, v0
	v_mov_b32_e32 v28, v0
	v_mov_b32_e32 v29, v0
	v_mov_b32_e32 v30, v0
	v_mov_b32_e32 v31, v0
	v_mov_b32_e32 v40, v0
	v_mov_b32_e32 v41, v0
	v_mov_b32_e32 v42, v0
	v_mov_b32_e32 v43, v0
	v_mov_b32_e32 v44, v0
	v_mov_b32_e32 v45, v0
	v_mov_b32_e32 v46, v0
	v_mov_b32_e32 v47, v0
	v_mov_b32_e32 v56, v0
	v_mov_b32_e32 v57, v0
	v_mov_b32_e32 v58, v0
	v_mov_b32_e32 v59, v0
	v_mov_b32_e32 v60, v0
	v_mov_b32_e32 v61, v0
	v_mov_b32_e32 v62, v0
	v_mov_b32_e32 v63, v0
	v_mov_b32_e32 v64, v0
	v_mov_b32_e32 v65, v0
	v_mov_b32_e32 v66, v0
	v_mov_b32_e32 v67, v0
	v_mov_b32_e32 v68, v0
	v_mov_b32_e32 v69, v0
	v_mov_b32_e32 v70, v0
	v_mov_b32_e32 v71, v0
	v_mov_b32_e32 v80, v0
	v_mov_b32_e32 v81, v0
	v_mov_b32_e32 v82, v0
	v_mov_b32_e32 v83, v0
	s_waitcnt vmcnt(0)
	v_mov_b32_e32 v84, v0
	v_mov_b32_e32 v85, v0
	v_mov_b32_e32 v86, v0
	v_mov_b32_e32 v87, v0
	v_mov_b32_e32 v96, v0
	v_mov_b32_e32 v97, v0
	v_mov_b32_e32 v98, v0
	v_mov_b32_e32 v99, v0
	v_mov_b32_e32 v100, v0
	v_mov_b32_e32 v101, v0
	v_mov_b32_e32 v102, v0
	v_mov_b32_e32 v103, v0
	v_mov_b32_e32 v128, v0
	v_mov_b32_e32 v129, v0
	v_mov_b32_e32 v130, v0
	v_mov_b32_e32 v131, v0
	v_mov_b32_e32 v132, v0
	v_mov_b32_e32 v133, v0
	v_mov_b32_e32 v134, v0
	v_mov_b32_e32 v135, v0
	v_mov_b32_e32 v72, v0
	v_mov_b32_e32 v73, v0
	v_mov_b32_e32 v74, v0
	v_mov_b32_e32 v75, v0
	v_mov_b32_e32 v76, v0
	v_mov_b32_e32 v77, v0
	v_mov_b32_e32 v78, v0
	v_mov_b32_e32 v79, v0
	v_mov_b32_e32 v88, v0
	v_mov_b32_e32 v89, v0
	v_mov_b32_e32 v90, v0
	v_mov_b32_e32 v91, v0
	v_mov_b32_e32 v92, v0
	v_mov_b32_e32 v93, v0
	v_mov_b32_e32 v94, v0
	v_mov_b32_e32 v95, v0
	v_mov_b32_e32 v112, v0
	v_mov_b32_e32 v113, v0
	v_mov_b32_e32 v114, v0
	v_mov_b32_e32 v115, v0
	v_mov_b32_e32 v116, v0
	v_mov_b32_e32 v117, v0
	v_mov_b32_e32 v118, v0
	v_mov_b32_e32 v119, v0
	v_mov_b32_e32 v136, v0
	v_mov_b32_e32 v137, v0
	v_mov_b32_e32 v138, v0
	v_mov_b32_e32 v139, v0
	v_mov_b32_e32 v140, v0
	v_mov_b32_e32 v141, v0
	v_mov_b32_e32 v142, v0
	v_mov_b32_e32 v143, v0
	s_barrier

.LBB0_1386:
	s_lshl_b64 s[12:13], s[66:67], 2
	s_add_u32 s12, s36, s12
	s_addc_u32 s13, s37, s13
	s_add_u32 s14, s12, 0x4c05000
	s_addc_u32 s15, s13, 0
	s_add_u32 s16, s36, 0x5370000
	v_readlane_b32 s20, v243, 58
	s_addc_u32 s17, s37, 0
	v_readlane_b32 s21, v243, 59
	s_and_b64 s[12:13], s[20:21], exec
	s_cselect_b32 s17, s17, 0
	s_cselect_b32 s16, s16, 0
	s_add_u32 s18, s36, 0x6570000
	s_addc_u32 s19, s37, 0
	s_and_b64 s[12:13], s[20:21], exec
	s_mov_b32 s12, 0x6250000
	s_cselect_b32 s12, s12, 0x6360000
	s_add_u32 s20, s36, s12
	s_addc_u32 s21, s37, 0
	v_bfe_u32 v16, v14, 4, 2
	s_cmp_lg_u32 s70, 1
	v_and_b32_e32 v15, 15, v14
	v_lshlrev_b32_e32 v18, 4, v16
	s_cselect_b64 s[72:73], -1, 0
	s_add_u32 s70, s36, 0x11688000
	v_lshl_or_b32 v224, s7, 6, v15
	v_lshl_or_b32 v18, v15, 6, v18
	v_lshlrev_b32_e32 v15, 2, v15
	s_addc_u32 s71, s37, 0
	s_lshl_b32 s12, s7, 13
	v_and_b32_e32 v19, 32, v15
	v_bitop3_b32 v20, v18, s12, v19 bitop3:0xde
	s_lshl_b32 s12, s22, 8
	s_and_b32 s1, s1, 3
	s_ashr_i32 s13, s12, 31
	s_lshl_b32 s26, s1, 12
	s_lshl_b64 s[12:13], s[12:13], 2
	s_add_u32 s27, s36, s12
	s_addc_u32 s28, s37, s13
	s_add_i32 m0, s74, 0x18000
	v_lshl_add_u64 v[4:5], v[4:5], 0, s[4:5]
	global_load_lds_dwordx4 v[4:5], off
	v_lshl_add_u64 v[2:3], v[2:3], 0, s[4:5]
	s_add_i32 m0, s74, 0x1a000
	s_add_i32 s12, s74, 0x8000
	s_add_i32 s13, s74, 0xa000
	global_load_lds_dwordx4 v[2:3], off
	v_lshl_add_u64 v[0:1], v[0:1], 0, s[4:5]
	s_mov_b32 m0, s12
	s_add_u32 s22, s80, 0x100080
	global_load_lds_dwordx4 v[0:1], off
	v_lshl_add_u64 v[0:1], v[6:7], 0, s[4:5]
	s_mov_b32 m0, s13
	s_addc_u32 s23, s81, 0
	global_load_lds_dwordx4 v[0:1], off
	s_add_i32 m0, s74, 0x1c000
	v_lshl_add_u64 v[0:1], s[22:23], 0, v[188:189]
	global_load_lds_dwordx4 v[0:1], off
	s_add_i32 m0, s74, 0x1e000
	s_cmpk_lt_u32 s6, 0x100
	v_lshl_add_u64 v[0:1], s[22:23], 0, v[192:193]
	s_cselect_b64 s[22:23], -1, 0
	s_or_b32 s6, s1, s7
	s_cmp_eq_u32 s6, 0
	s_cselect_b64 s[24:25], -1, 0
	s_lshl_b32 s6, s7, 14
	s_or_b32 s6, s26, s6
	s_ashr_i32 s7, s6, 31
	s_lshl_b64 s[6:7], s[6:7], 2
	s_add_u32 s6, s36, s6
	v_readlane_b32 s30, v243, 27
	v_writelane_b32 v242, s36, 0
	s_addc_u32 s7, s37, s7
	s_add_u32 s6, s6, 0xbe70000
	s_addc_u32 s7, s7, 0
	v_bitop3_b32 v225, v18, s26, v19 bitop3:0xde
	v_readlane_b32 s31, v243, 28
	s_add_u32 s26, s27, s30
	s_addc_u32 s27, s28, s31
	s_add_u32 s26, s26, 0x11084000
	s_addc_u32 s27, s27, 0
	v_readlane_b32 s28, v244, 37
	v_readlane_b32 s29, v244, 38
	s_add_u32 s28, s6, s28
	s_addc_u32 s29, s7, s29
	s_add_u32 s30, s28, 0x400
	v_writelane_b32 v242, s37, 1
	s_addc_u32 s31, s29, 0
	v_writelane_b32 v242, s30, 2
	global_load_lds_dwordx4 v[0:1], off
	s_waitcnt vmcnt(8)
	s_barrier
	s_nop 0
	v_writelane_b32 v242, s31, 3
	s_add_u32 s30, s28, 0x800
	s_addc_u32 s31, s29, 0
	v_writelane_b32 v242, s30, 4
	v_lshlrev_b32_e32 v2, 16, v8
	v_and_b32_e32 v2, 0xfffe0000, v2
	v_writelane_b32 v242, s31, 5
	s_add_u32 s30, s28, 0xc00
	s_addc_u32 s31, s29, 0
	v_writelane_b32 v242, s30, 6
	v_lshl_add_u32 v2, v9, 13, v2
	v_and_b32_e32 v3, 1, v8
	v_writelane_b32 v242, s31, 7
	s_add_u32 s30, s28, 0x1000
	s_addc_u32 s31, s29, 0
	v_writelane_b32 v242, s30, 8
	v_lshl_or_b32 v2, v3, 6, v2
	v_lshl_add_u32 v196, v10, 1, v2
	v_writelane_b32 v242, s31, 9
	s_add_u32 s30, s28, 0x1400
	s_addc_u32 s31, s29, 0
	v_writelane_b32 v242, s30, 10
	v_lshlrev_b32_e32 v2, 16, v11
	v_and_b32_e32 v2, 0xfffe0000, v2
	v_writelane_b32 v242, s31, 11
	s_add_u32 s30, s28, 0x1800
	s_addc_u32 s31, s29, 0
	v_writelane_b32 v242, s30, 12
	s_waitcnt vmcnt(6)
	v_and_b32_e32 v1, 63, v14
	v_lshl_add_u32 v2, v12, 13, v2
	v_writelane_b32 v242, s31, 13
	s_add_u32 s30, s28, 0x1c00
	s_addc_u32 s31, s29, 0
	s_add_u32 s46, s28, 0x2000
	s_addc_u32 s47, s29, 0
	s_add_u32 s48, s28, 0x2400
	s_addc_u32 s49, s29, 0
	s_add_u32 s50, s28, 0x2800
	s_addc_u32 s51, s29, 0
	s_add_u32 s52, s28, 0x2c00
	s_addc_u32 s53, s29, 0
	s_add_u32 s54, s28, 0x3000
	s_addc_u32 s55, s29, 0
	s_add_u32 s56, s28, 0x3400
	s_addc_u32 s57, s29, 0
	s_add_u32 s58, s28, 0x3800
	v_writelane_b32 v242, s30, 14
	s_addc_u32 s59, s29, 0
	s_add_u32 s60, s28, 0x3c00
	v_writelane_b32 v242, s31, 15
	v_readlane_b32 s30, v243, 56
	s_addc_u32 s61, s29, 0
	s_lshl_b32 s92, s30, 9
	s_addk_i32 s92, 0x2000
	s_lshl_b32 s93, s30, 13
	v_readlane_b32 s30, v244, 35
	v_readlane_b32 s31, v244, 36
	s_add_u32 s62, s6, s30
	s_addc_u32 s63, s7, s31
	s_add_u32 s6, s62, 0x1000
	s_addc_u32 s7, s63, 0
	v_writelane_b32 v242, s6, 16
	v_and_b32_e32 v3, 1, v11
	v_lshlrev_b32_e32 v17, 3, v16
	v_writelane_b32 v242, s7, 17
	s_add_u32 s6, s62, 0x400
	s_addc_u32 s7, s63, 0
	v_writelane_b32 v242, s6, 18
	v_lshlrev_b32_e32 v0, 2, v1
	v_lshl_or_b32 v2, v3, 6, v2
	v_writelane_b32 v242, s7, 19
	s_add_u32 s6, s62, 0x1400
	s_addc_u32 s7, s63, 0
	v_writelane_b32 v242, s6, 20
	v_lshl_or_b32 v226, s1, 5, v17
	v_lshl_or_b32 v194, v16, 6, v15
	v_writelane_b32 v242, s7, 21
	s_add_u32 s6, s62, 0x800
	s_addc_u32 s7, s63, 0
	v_writelane_b32 v242, s6, 22
	v_or_b32_e32 v227, 16, v224
	v_or_b32_e32 v228, 32, v224
	v_writelane_b32 v242, s7, 23
	s_add_u32 s6, s62, 0x1800
	s_addc_u32 s7, s63, 0
	v_writelane_b32 v242, s6, 24
	v_or_b32_e32 v229, 48, v224
	v_add_u32_e32 v230, 0x80, v224
	v_writelane_b32 v242, s7, 25
	s_add_u32 s6, s62, 0xc00
	s_addc_u32 s7, s63, 0
	v_writelane_b32 v242, s6, 26
	v_add_u32_e32 v231, 0x90, v224
	v_add_u32_e32 v232, 0xa0, v224
	v_writelane_b32 v242, s7, 27
	s_add_u32 s6, s62, 0x1c00
	s_addc_u32 s7, s63, 0
	v_writelane_b32 v242, s6, 28
	v_add_u32_e32 v233, 0xb0, v224
	v_mov_b32_e32 v197, v185
	v_writelane_b32 v242, s7, 29
	s_add_u32 s6, s62, 0x2000
	s_addc_u32 s7, s63, 0
	v_writelane_b32 v242, s6, 30
	v_lshl_add_u32 v198, v13, 1, v2
	v_mov_b32_e32 v199, v185
	v_writelane_b32 v242, s7, 31
	s_add_u32 s6, s62, 0x3000
	s_addc_u32 s7, s63, 0
	v_writelane_b32 v242, s6, 32
	v_add_u32_e32 v234, 0, v20
	v_lshlrev_b32_e32 v184, 2, v0
	v_writelane_b32 v242, s7, 33
	s_add_u32 s6, s62, 0x2400
	s_addc_u32 s7, s63, 0
	v_writelane_b32 v242, s6, 34
	s_mov_b32 s94, 0
	v_readlane_b32 s34, v244, 55
	v_writelane_b32 v242, s7, 35
	s_add_u32 s6, s62, 0x3400
	s_addc_u32 s7, s63, 0
	v_writelane_b32 v242, s6, 36
	v_readlane_b32 s35, v244, 40
	v_readlane_b32 s95, v244, 44
	v_writelane_b32 v242, s7, 37
	s_add_u32 s6, s62, 0x2800
	s_addc_u32 s7, s63, 0
	v_writelane_b32 v242, s6, 38
	v_readlane_b32 s30, v244, 54
	v_cmp_eq_u32_e64 s[76:77], 0, v16
	v_writelane_b32 v242, s7, 39
	s_add_u32 s6, s62, 0x3800
	s_addc_u32 s7, s63, 0
	v_writelane_b32 v242, s6, 40
	s_barrier
	s_nop 0
	v_writelane_b32 v242, s7, 41
	s_add_u32 s6, s62, 0x2c00
	s_addc_u32 s7, s63, 0
	v_writelane_b32 v242, s6, 42
	s_nop 1
	v_writelane_b32 v242, s7, 43
	s_add_u32 s6, s62, 0x3c00
	s_addc_u32 s7, s63, 0
	v_writelane_b32 v242, s6, 44
	s_nop 1
	v_writelane_b32 v242, s7, 45
	v_readlane_b32 s6, v244, 46
	v_readlane_b32 s7, v244, 47
	s_mov_b32 s31, s6
	v_cmp_eq_u32_e64 s[6:7], 0, v1
	s_nop 1
	v_writelane_b32 v242, s6, 46
	s_nop 1
	v_writelane_b32 v242, s7, 47
	s_branch .LBB0_1389
